# weight prep in the prep phase: contiguous per-wave tile ranges over one unified tile list (13 tiles per wave, 4 in flight) instead of per-matrix strided loops
# baseline (speedup 1.0000x reference)
.Lwp_entry:
	s_mov_b64 s[84:85], s[0:1]
	s_mov_b32 s86, s18
	s_mov_b32 s87, s19
	s_mov_b64 s[88:89], s[22:23]
	s_mov_b64 s[92:93], s[26:27]
	s_mov_b64 s[94:95], s[30:31]
	v_mov_b32_e32 v120, v0
	v_mov_b32_e32 v121, v1
	v_mov_b32_e32 v122, v57
	s_load_dwordx8 s[52:59], s[0:1], 0x40
	s_waitcnt lgkmcnt(0)
	s_waitcnt vmcnt(0)
	v_and_b32_e32 v105, 15, v143
	v_bfe_u32 v106, v143, 4, 2
	v_lshlrev_b32_e32 v107, 5, v106
	v_mov_b32_e32 v108, 0
	v_mov_b32_e32 v109, 0
	v_mov_b32_e32 v110, 0
	v_mov_b32_e32 v111, 0
	v_readfirstlane_b32 s0, v143
	s_lshr_b32 s0, s0, 6
	v_readlane_b32 s1, v253, 0
	s_sub_u32 s1, s1, 96
	s_lshl_b32 s1, s1, 3
	s_add_i32 s21, s1, s0
	s_movk_i32 s19, 1
	s_mul_i32 s34, s21, 13
	s_add_u32 s35, s34, 13
	s_min_u32 s35, s35, 16640
	s_max_u32 s0, s34, 0
	s_min_u32 s1, s35, 5632
	s_cmp_lt_u32 s0, s1
	s_cbranch_scc0 .Lwp_ret_0
	s_sub_u32 s33, s0, 0
	s_sub_u32 s28, s1, 0
	v_readlane_b32 s4, v253, 15
	v_readlane_b32 s5, v253, 16
	s_add_u32 s6, s50, 0
	s_addc_u32 s7, s51, 0
	s_mov_b32 s8, 10368
	s_mov_b32 s9, 2048
	s_mov_b32 s10, 176
	s_mov_b32 s11, s28
	s_mov_b32 s12, 0x1745d18
	s_mov_b32 s13, 0
	s_mov_b32 s16, 162
	s_mov_b64 s[14:15], 0
	s_mov_b32 s20, 0
	s_branch .Lwp_mat
.Lwp_ret_0:
	s_max_u32 s0, s34, 5632
	s_min_u32 s1, s35, 5952
	s_cmp_lt_u32 s0, s1
	s_cbranch_scc0 .Lwp_ret_1
	s_sub_u32 s33, s0, 5632
	s_sub_u32 s28, s1, 5632
	s_mov_b64 s[4:5], s[54:55]
	s_add_u32 s6, s50, 11534336
	s_addc_u32 s7, s51, 0
	s_mov_b32 s8, 2304
	s_mov_b32 s9, 512
	s_mov_b32 s10, 40
	s_mov_b32 s11, s28
	s_mov_b32 s12, 0x6666667
	s_mov_b32 s13, 0
	s_mov_b32 s16, 36
	s_mov_b64 s[14:15], s[52:53]
	s_mov_b32 s20, 1
	s_branch .Lwp_mat
.Lwp_ret_1:
	s_max_u32 s0, s34, 5952
	s_min_u32 s1, s35, 6144
	s_cmp_lt_u32 s0, s1
	s_cbranch_scc0 .Lwp_ret_2
	s_sub_u32 s33, s0, 5952
	s_sub_u32 s28, s1, 5952
	s_mov_b64 s[4:5], s[58:59]
	s_add_u32 s6, s50, 12189696
	s_addc_u32 s7, s51, 0
	s_mov_b32 s8, 3072
	s_mov_b32 s9, 256
	s_mov_b32 s10, 48
	s_mov_b32 s11, s28
	s_mov_b32 s12, 0x5555556
	s_mov_b32 s13, 0
	s_mov_b32 s16, 48
	s_mov_b64 s[14:15], s[56:57]
	s_mov_b32 s20, 2
	s_branch .Lwp_mat
.Lwp_ret_2:
	s_max_u32 s0, s34, 6144
	s_min_u32 s1, s35, 6272
	s_cmp_lt_u32 s0, s1
	s_cbranch_scc0 .Lwp_ret_3
	s_sub_u32 s33, s0, 6144
	s_sub_u32 s28, s1, 6144
	s_mov_b64 s[4:5], s[40:41]
	s_add_u32 s6, s50, 12582912
	s_addc_u32 s7, s51, 0
	s_mov_b32 s8, 1024
	s_mov_b32 s9, 512
	s_mov_b32 s10, 16
	s_mov_b32 s11, s28
	s_mov_b32 s12, 0x10000000
	s_mov_b32 s13, 0
	s_mov_b32 s16, 16
	s_mov_b64 s[14:15], 0
	s_mov_b32 s20, 3
	s_branch .Lwp_mat
.Lwp_ret_3:
	s_max_u32 s0, s34, 6272
	s_min_u32 s1, s35, 8320
	s_cmp_lt_u32 s0, s1
	s_cbranch_scc0 .Lwp_ret_4
	s_sub_u32 s33, s0, 6272
	s_sub_u32 s28, s1, 6272
	s_mov_b64 s[4:5], s[44:45]
	s_add_u32 s6, s50, 12845056
	s_addc_u32 s7, s51, 0
	s_mov_b32 s8, 4096
	s_mov_b32 s9, 2048
	s_mov_b32 s10, 64
	s_mov_b32 s11, s28
	s_mov_b32 s12, 0x4000000
	s_mov_b32 s13, 0
	s_mov_b32 s16, 64
	s_mov_b64 s[14:15], 0
	s_mov_b32 s20, 4
	s_branch .Lwp_mat
.Lwp_ret_4:
	s_max_u32 s0, s34, 8320
	s_min_u32 s1, s35, 13952
	s_cmp_lt_u32 s0, s1
	s_cbranch_scc0 .Lwp_ret_5
	s_sub_u32 s33, s0, 8320
	s_sub_u32 s28, s1, 8320
	v_readlane_b32 s4, v253, 15
	v_readlane_b32 s5, v253, 16
	s_add_u32 s4, s4, 10616832
	s_addc_u32 s5, s5, 0
	s_add_u32 s6, s50, 5767168
	s_addc_u32 s7, s51, 0
	s_mov_b32 s8, 10368
	s_mov_b32 s9, 2048
	s_mov_b32 s10, 176
	s_mov_b32 s11, s28
	s_mov_b32 s12, 0x1745d18
	s_mov_b32 s13, 0
	s_mov_b32 s16, 162
	s_mov_b64 s[14:15], 0
	s_mov_b32 s20, 5
	s_branch .Lwp_mat
.Lwp_ret_5:
	s_max_u32 s0, s34, 13952
	s_min_u32 s1, s35, 14272
	s_cmp_lt_u32 s0, s1
	s_cbranch_scc0 .Lwp_ret_6
	s_sub_u32 s33, s0, 13952
	s_sub_u32 s28, s1, 13952
	s_mov_b64 s[4:5], s[54:55]
	s_add_u32 s4, s4, 589824
	s_addc_u32 s5, s5, 0
	s_add_u32 s6, s50, 11862016
	s_addc_u32 s7, s51, 0
	s_mov_b32 s8, 2304
	s_mov_b32 s9, 512
	s_mov_b32 s10, 40
	s_mov_b32 s11, s28
	s_mov_b32 s12, 0x6666667
	s_mov_b32 s13, 0
	s_mov_b32 s16, 36
	s_mov_b64 s[14:15], s[52:53]
	s_add_u32 s14, s14, 1024
	s_addc_u32 s15, s15, 0
	s_mov_b32 s20, 6
	s_branch .Lwp_mat
.Lwp_ret_6:
	s_max_u32 s0, s34, 14272
	s_min_u32 s1, s35, 14464
	s_cmp_lt_u32 s0, s1
	s_cbranch_scc0 .Lwp_ret_7
	s_sub_u32 s33, s0, 14272
	s_sub_u32 s28, s1, 14272
	s_mov_b64 s[4:5], s[58:59]
	s_add_u32 s4, s4, 393216
	s_addc_u32 s5, s5, 0
	s_add_u32 s6, s50, 12386304
	s_addc_u32 s7, s51, 0
	s_mov_b32 s8, 3072
	s_mov_b32 s9, 256
	s_mov_b32 s10, 48
	s_mov_b32 s11, s28
	s_mov_b32 s12, 0x5555556
	s_mov_b32 s13, 0
	s_mov_b32 s16, 48
	s_mov_b64 s[14:15], s[56:57]
	s_add_u32 s14, s14, 512
	s_addc_u32 s15, s15, 0
	s_mov_b32 s20, 7
	s_branch .Lwp_mat
.Lwp_ret_7:
	s_max_u32 s0, s34, 14464
	s_min_u32 s1, s35, 14592
	s_cmp_lt_u32 s0, s1
	s_cbranch_scc0 .Lwp_ret_8
	s_sub_u32 s33, s0, 14464
	s_sub_u32 s28, s1, 14464
	s_mov_b64 s[4:5], s[40:41]
	s_add_u32 s4, s4, 262144
	s_addc_u32 s5, s5, 0
	s_add_u32 s6, s50, 12713984
	s_addc_u32 s7, s51, 0
	s_mov_b32 s8, 1024
	s_mov_b32 s9, 512
	s_mov_b32 s10, 16
	s_mov_b32 s11, s28
	s_mov_b32 s12, 0x10000000
	s_mov_b32 s13, 0
	s_mov_b32 s16, 16
	s_mov_b64 s[14:15], 0
	s_mov_b32 s20, 8
	s_branch .Lwp_mat
.Lwp_ret_8:
	s_max_u32 s0, s34, 14592
	s_min_u32 s1, s35, 16640
	s_cmp_lt_u32 s0, s1
	s_cbranch_scc0 .Lwp_ret_9
	s_sub_u32 s33, s0, 14592
	s_sub_u32 s28, s1, 14592
	s_mov_b64 s[4:5], s[44:45]
	s_add_u32 s4, s4, 4194304
	s_addc_u32 s5, s5, 0
	s_add_u32 s6, s50, 14942208
	s_addc_u32 s7, s51, 0
	s_mov_b32 s8, 4096
	s_mov_b32 s9, 2048
	s_mov_b32 s10, 64
	s_mov_b32 s11, s28
	s_mov_b32 s12, 0x4000000
	s_mov_b32 s13, 0
	s_mov_b32 s16, 64
	s_mov_b64 s[14:15], 0
	s_mov_b32 s20, 9
	s_branch .Lwp_mat

.Lwp_mat:
	v_lshlrev_b32_e32 v104, 3, v106
	v_mul_lo_u32 v96, s8, v104
	v_lshl_add_u32 v96, v105, 2, v96
	v_add_u32_e32 v97, s8, v96
	v_add_u32_e32 v98, s8, v97
	v_add_u32_e32 v99, s8, v98
	v_add_u32_e32 v100, s8, v99
	v_add_u32_e32 v101, s8, v100
	v_add_u32_e32 v102, s8, v101
	v_add_u32_e32 v103, s8, v102
	v_mul_lo_u32 v112, s9, v105
	v_lshl_add_u32 v104, v104, 1, v112
	s_mov_b32 s18, s33
